# flash next-tile K/V load addresses: 8 add_co/addc pairs + carry nops folded into 4 scalar constant adds + 4 v_lshl_add_u64 with -4096 immediate offsets
# speedup vs baseline: 1.0006x; 1.0002x over previous
.LBB0_855:
	v_add_u32_e32 v0, 0x4800, v190
	v_readlane_b32 s0, v251, 29
	s_barrier
	s_waitcnt vmcnt(0)
	ds_write_b128 v188, v[128:131]
	ds_write_b128 v188, v[132:135] offset:4608
	ds_write_b128 v188, v[144:147] offset:9216
	ds_write_b128 v188, v[156:159] offset:13824
	ds_write2_b64 v0, v[140:141], v[142:143] offset1:1
	v_add_u32_e32 v0, 0x5880, v190
	s_cmp_ge_u32 s0, s23
	ds_write2_b64 v0, v[136:137], v[138:139] offset1:1
	v_add_u32_e32 v0, 0x6900, v190
	s_cselect_b64 s[16:17], -1, 0
	ds_write2_b64 v0, v[152:153], v[154:155] offset1:1
	v_add_u32_e32 v0, 0x7980, v190
	s_and_b64 vcc, exec, s[16:17]
	ds_write2_b64 v0, v[148:149], v[150:151] offset1:1
	s_waitcnt lgkmcnt(0)
	s_barrier
	v_readlane_b32 s1, v251, 30
	s_cbranch_vccnz .LBB0_857
	s_add_u32 s2, s14, 0x5000
	s_addc_u32 s3, s15, 0
	v_lshl_add_u64 v[0:1], v[192:193], 0, s[2:3]
	s_add_u32 s2, s14, 0x7000
	s_addc_u32 s3, s15, 0
	v_lshl_add_u64 v[2:3], v[192:193], 0, s[2:3]
	s_add_u32 s2, s14, 0x805000
	s_addc_u32 s3, s15, 0
	v_lshl_add_u64 v[4:5], v[194:195], 0, s[2:3]
	global_load_dwordx4 v[128:131], v[0:1], off offset:-4096
	global_load_dwordx4 v[132:135], v[0:1], off
	s_add_u32 s2, s14, 0x807000
	s_addc_u32 s3, s15, 0
	global_load_dwordx4 v[144:147], v[2:3], off offset:-4096
	global_load_dwordx4 v[156:159], v[2:3], off
	v_lshl_add_u64 v[0:1], v[194:195], 0, s[2:3]
	global_load_dwordx4 v[140:143], v[4:5], off offset:-4096
	global_load_dwordx4 v[136:139], v[4:5], off
	global_load_dwordx4 v[152:155], v[0:1], off offset:-4096
	global_load_dwordx4 v[148:151], v[0:1], off
